# LayerNorm phases: the 16 gain / bias / modulation loads of a row issued together instead of four dependent load-wait-store round trips
# baseline (speedup 1.0000x reference)
.LBB0_936:
	s_or_b64 exec, exec, s[4:5]
	v_cndmask_b32_e64 v15, v42, 4, s[12:13]
	v_mul_hi_i32_i24_e32 v43, 0x6000, v15
	v_mul_i32_i24_e32 v42, 0x6000, v15
	v_lshl_add_u64 v[54:55], s[8:9], 0, v[42:43]
	v_lshl_add_u64 v[58:59], v[54:55], 0, s[20:21]
	v_lshl_add_u64 v[50:51], v[58:59], 0, v[24:25]
	global_load_dwordx4 v[64:67], v[16:17], off
	global_load_dwordx4 v[68:71], v[18:19], off
	v_lshl_add_u64 v[60:61], v[54:55], 0, v[24:25]
	global_load_dwordx4 v[72:75], v[50:51], off
	v_pk_mul_f32 v[32:33], v[32:33], v[14:15] op_sel_hi:[1,0]
	global_load_dwordx4 v[76:79], v[60:61], off
	v_lshl_add_u64 v[132:133], v[58:59], 0, v[26:27]
	v_lshl_add_u64 v[134:135], v[58:59], 0, v[28:29]
	v_lshl_add_u64 v[136:137], v[58:59], 0, v[30:31]
	global_load_dwordx4 v[80:83], v[16:17], off offset:1024
	global_load_dwordx4 v[84:87], v[18:19], off offset:1024
	global_load_dwordx4 v[88:91], v[132:133], off
	global_load_dwordx4 v[92:95], v[60:61], off offset:1024
	global_load_dwordx4 v[96:99], v[16:17], off offset:2048
	global_load_dwordx4 v[100:103], v[18:19], off offset:2048
	global_load_dwordx4 v[104:107], v[134:135], off
	global_load_dwordx4 v[108:111], v[60:61], off offset:2048
	global_load_dwordx4 v[112:115], v[16:17], off offset:3072
	global_load_dwordx4 v[116:119], v[18:19], off offset:3072
	global_load_dwordx4 v[120:123], v[136:137], off
	global_load_dwordx4 v[124:127], v[60:61], off offset:3072
	v_pk_mul_f32 v[12:13], v[12:13], v[14:15] op_sel_hi:[1,0]
	v_lshl_add_u64 v[62:63], s[90:91], 0, v[22:23]
	v_add_co_u32_e32 v62, vcc, s7, v62
	v_pk_mul_f32 v[10:11], v[10:11], v[14:15] op_sel_hi:[1,0]
	s_nop 0
	v_addc_co_u32_e32 v63, vcc, 0, v63, vcc
	v_pk_mul_f32 v[8:9], v[8:9], v[14:15] op_sel_hi:[1,0]
	v_pk_mul_f32 v[6:7], v[6:7], v[14:15] op_sel_hi:[1,0]
	v_pk_mul_f32 v[4:5], v[4:5], v[14:15] op_sel_hi:[1,0]
	v_pk_mul_f32 v[2:3], v[2:3], v[14:15] op_sel_hi:[1,0]
	v_pk_mul_f32 v[0:1], v[0:1], v[14:15] op_sel_hi:[1,0]
	v_add_u32_e32 v41, s52, v41
	v_cmp_lt_i32_e32 vcc, s22, v41
	v_lshl_add_u64 v[20:21], v[20:21], 0, s[14:15]
	s_or_b64 s[18:19], vcc, s[18:19]
	v_lshl_add_u64 v[22:23], v[22:23], 0, s[16:17]
	s_waitcnt vmcnt(14)
	v_pk_fma_f32 v[32:33], v[32:33], v[66:67], v[70:71]
	v_pk_fma_f32 v[12:13], v[12:13], v[64:65], v[68:69]
	s_waitcnt vmcnt(13)
	v_pk_add_f32 v[42:43], v[74:75], 1.0 op_sel_hi:[1,0]
	v_pk_add_f32 v[44:45], v[72:73], 1.0 op_sel_hi:[1,0]
	s_waitcnt vmcnt(12)
	v_pk_fma_f32 v[32:33], v[32:33], v[42:43], v[78:79]
	v_pk_fma_f32 v[12:13], v[12:13], v[44:45], v[76:77]
	s_nop 0
	v_cvt_pk_bf16_f32 v12, v12, v13
	v_cvt_pk_bf16_f32 v13, v32, v33
	global_store_dwordx2 v[62:63], v[12:13], off
	v_lshl_add_u64 v[12:13], v[58:59], 0, v[26:27]
	s_waitcnt vmcnt(11)
	v_pk_fma_f32 v[10:11], v[10:11], v[82:83], v[86:87]
	v_pk_fma_f32 v[8:9], v[8:9], v[80:81], v[84:85]
	s_waitcnt vmcnt(10)
	v_pk_add_f32 v[12:13], v[90:91], 1.0 op_sel_hi:[1,0]
	v_pk_add_f32 v[32:33], v[88:89], 1.0 op_sel_hi:[1,0]
	s_waitcnt vmcnt(9)
	v_pk_fma_f32 v[10:11], v[10:11], v[12:13], v[94:95]
	v_pk_fma_f32 v[8:9], v[8:9], v[32:33], v[92:93]
	v_lshl_add_u64 v[12:13], v[58:59], 0, v[28:29]
	v_cvt_pk_bf16_f32 v8, v8, v9
	v_cvt_pk_bf16_f32 v9, v10, v11
	global_store_dwordx2 v[62:63], v[8:9], off offset:512
	s_nop 0
	v_lshl_add_u64 v[12:13], v[58:59], 0, v[30:31]
	s_waitcnt vmcnt(8)
	v_pk_fma_f32 v[6:7], v[6:7], v[98:99], v[102:103]
	v_pk_fma_f32 v[4:5], v[4:5], v[96:97], v[100:101]
	s_waitcnt vmcnt(7)
	v_pk_add_f32 v[8:9], v[106:107], 1.0 op_sel_hi:[1,0]
	v_pk_add_f32 v[10:11], v[104:105], 1.0 op_sel_hi:[1,0]
	s_waitcnt vmcnt(6)
	v_pk_fma_f32 v[6:7], v[6:7], v[8:9], v[110:111]
	v_pk_fma_f32 v[4:5], v[4:5], v[10:11], v[108:109]
	s_nop 0
	v_cvt_pk_bf16_f32 v4, v4, v5
	v_cvt_pk_bf16_f32 v5, v6, v7
	global_store_dwordx2 v[62:63], v[4:5], off offset:1024
	s_nop 0
	s_waitcnt vmcnt(5)
	v_pk_fma_f32 v[2:3], v[2:3], v[114:115], v[118:119]
	v_pk_fma_f32 v[0:1], v[0:1], v[112:113], v[116:117]
	s_waitcnt vmcnt(4)
	v_pk_add_f32 v[4:5], v[122:123], 1.0 op_sel_hi:[1,0]
	v_pk_add_f32 v[6:7], v[120:121], 1.0 op_sel_hi:[1,0]
	s_waitcnt vmcnt(3)
	v_pk_fma_f32 v[2:3], v[2:3], v[4:5], v[126:127]
	v_pk_fma_f32 v[0:1], v[0:1], v[6:7], v[124:125]
	s_nop 0
	v_cvt_pk_bf16_f32 v0, v0, v1
	v_cvt_pk_bf16_f32 v1, v2, v3
	global_store_dwordx2 v[62:63], v[0:1], off offset:1536
	s_andn2_b64 exec, exec, s[18:19]
	s_cbranch_execz .LBB0_943

.LBB0_1256:
	s_or_b64 exec, exec, s[4:5]
	v_readlane_b32 s16, v254, 28
	v_add_u32_e32 v15, 5, v54
	v_readlane_b32 s17, v254, 29
	v_readlane_b32 s18, v254, 30
	v_readlane_b32 s19, v254, 31
	v_readlane_b32 s20, v254, 32
	v_readlane_b32 s21, v254, 33
	v_cndmask_b32_e64 v15, v15, 9, s[12:13]
	v_readlane_b32 s22, v254, 34
	v_readlane_b32 s23, v254, 35
	s_mov_b64 s[16:17], s[20:21]
	v_mul_hi_i32_i24_e32 v55, 0x6000, v15
	v_mul_i32_i24_e32 v54, 0x6000, v15
	s_mov_b64 s[18:19], s[22:23]
	v_lshl_add_u64 v[66:67], s[18:19], 0, v[54:55]
	s_mov_b64 s[4:5], 0x1000
	v_lshl_add_u64 v[70:71], v[66:67], 0, s[4:5]
	v_lshl_add_u64 v[62:63], v[70:71], 0, v[36:37]
	global_load_dwordx4 v[76:79], v[16:17], off
	global_load_dwordx4 v[80:83], v[18:19], off
	v_lshl_add_u64 v[72:73], v[66:67], 0, v[36:37]
	global_load_dwordx4 v[84:87], v[62:63], off
	v_pk_mul_f32 v[44:45], v[44:45], v[14:15] op_sel_hi:[1,0]
	global_load_dwordx4 v[88:91], v[72:73], off
	v_lshl_add_u64 v[140:141], v[70:71], 0, v[38:39]
	v_lshl_add_u64 v[142:143], v[70:71], 0, v[40:41]
	v_lshl_add_u64 v[160:161], v[70:71], 0, v[42:43]
	global_load_dwordx4 v[92:95], v[20:21], off
	global_load_dwordx4 v[96:99], v[22:23], off
	global_load_dwordx4 v[100:103], v[140:141], off
	global_load_dwordx4 v[104:107], v[72:73], off offset:1024
	global_load_dwordx4 v[108:111], v[24:25], off
	global_load_dwordx4 v[112:115], v[26:27], off
	global_load_dwordx4 v[116:119], v[142:143], off
	global_load_dwordx4 v[120:123], v[72:73], off offset:2048
	global_load_dwordx4 v[124:127], v[28:29], off
	global_load_dwordx4 v[128:131], v[30:31], off
	global_load_dwordx4 v[132:135], v[160:161], off
	global_load_dwordx4 v[136:139], v[72:73], off offset:3072
	v_pk_mul_f32 v[12:13], v[12:13], v[14:15] op_sel_hi:[1,0]
	v_lshl_add_u64 v[74:75], s[18:19], 0, v[34:35]
	v_add_co_u32_e32 v74, vcc, s27, v74
	v_pk_mul_f32 v[10:11], v[10:11], v[14:15] op_sel_hi:[1,0]
	s_nop 0
	v_addc_co_u32_e32 v75, vcc, 0, v75, vcc
	v_pk_mul_f32 v[8:9], v[8:9], v[14:15] op_sel_hi:[1,0]
	v_pk_mul_f32 v[6:7], v[6:7], v[14:15] op_sel_hi:[1,0]
	v_pk_mul_f32 v[4:5], v[4:5], v[14:15] op_sel_hi:[1,0]
	v_pk_mul_f32 v[2:3], v[2:3], v[14:15] op_sel_hi:[1,0]
	v_pk_mul_f32 v[0:1], v[0:1], v[14:15] op_sel_hi:[1,0]
	v_add_u32_e32 v53, s52, v53
	v_cmp_lt_i32_e32 vcc, s28, v53
	v_lshl_add_u64 v[32:33], v[32:33], 0, s[8:9]
	s_or_b64 s[24:25], vcc, s[24:25]
	v_lshl_add_u64 v[34:35], v[34:35], 0, s[14:15]
	s_waitcnt vmcnt(14)
	v_pk_fma_f32 v[44:45], v[44:45], v[78:79], v[82:83]
	v_pk_fma_f32 v[12:13], v[12:13], v[76:77], v[80:81]
	s_waitcnt vmcnt(13)
	v_pk_add_f32 v[54:55], v[86:87], 1.0 op_sel_hi:[1,0]
	v_pk_add_f32 v[56:57], v[84:85], 1.0 op_sel_hi:[1,0]
	s_waitcnt vmcnt(12)
	v_pk_fma_f32 v[44:45], v[44:45], v[54:55], v[90:91]
	v_pk_fma_f32 v[12:13], v[12:13], v[56:57], v[88:89]
	s_nop 0
	v_cvt_pk_bf16_f32 v12, v12, v13
	v_cvt_pk_bf16_f32 v13, v44, v45
	global_store_dwordx2 v[74:75], v[12:13], off
	v_lshl_add_u64 v[12:13], v[70:71], 0, v[38:39]
	s_waitcnt vmcnt(11)
	v_pk_fma_f32 v[10:11], v[10:11], v[94:95], v[98:99]
	v_pk_fma_f32 v[8:9], v[8:9], v[92:93], v[96:97]
	s_waitcnt vmcnt(10)
	v_pk_add_f32 v[12:13], v[102:103], 1.0 op_sel_hi:[1,0]
	v_pk_add_f32 v[44:45], v[100:101], 1.0 op_sel_hi:[1,0]
	s_waitcnt vmcnt(9)
	v_pk_fma_f32 v[10:11], v[10:11], v[12:13], v[106:107]
	v_pk_fma_f32 v[8:9], v[8:9], v[44:45], v[104:105]
	v_lshl_add_u64 v[12:13], v[70:71], 0, v[40:41]
	v_cvt_pk_bf16_f32 v8, v8, v9
	v_cvt_pk_bf16_f32 v9, v10, v11
	global_store_dwordx2 v[74:75], v[8:9], off offset:512
	s_nop 0
	v_lshl_add_u64 v[12:13], v[70:71], 0, v[42:43]
	s_waitcnt vmcnt(8)
	v_pk_fma_f32 v[6:7], v[6:7], v[110:111], v[114:115]
	v_pk_fma_f32 v[4:5], v[4:5], v[108:109], v[112:113]
	s_waitcnt vmcnt(7)
	v_pk_add_f32 v[8:9], v[118:119], 1.0 op_sel_hi:[1,0]
	v_pk_add_f32 v[10:11], v[116:117], 1.0 op_sel_hi:[1,0]
	s_waitcnt vmcnt(6)
	v_pk_fma_f32 v[6:7], v[6:7], v[8:9], v[122:123]
	v_pk_fma_f32 v[4:5], v[4:5], v[10:11], v[120:121]
	s_nop 0
	v_cvt_pk_bf16_f32 v4, v4, v5
	v_cvt_pk_bf16_f32 v5, v6, v7
	global_store_dwordx2 v[74:75], v[4:5], off offset:1024
	s_nop 0
	s_waitcnt vmcnt(5)
	v_pk_fma_f32 v[2:3], v[2:3], v[126:127], v[130:131]
	v_pk_fma_f32 v[0:1], v[0:1], v[124:125], v[128:129]
	s_waitcnt vmcnt(4)
	v_pk_add_f32 v[4:5], v[134:135], 1.0 op_sel_hi:[1,0]
	v_pk_add_f32 v[6:7], v[132:133], 1.0 op_sel_hi:[1,0]
	s_waitcnt vmcnt(3)
	v_pk_fma_f32 v[2:3], v[2:3], v[4:5], v[138:139]
	v_pk_fma_f32 v[0:1], v[0:1], v[6:7], v[136:137]
	s_nop 0
	v_cvt_pk_bf16_f32 v0, v0, v1
	v_cvt_pk_bf16_f32 v1, v2, v3
	global_store_dwordx2 v[74:75], v[0:1], off offset:1536
	s_andn2_b64 exec, exec, s[24:25]
	s_cbranch_execz .LBB0_1263

.LBB0_1846:
	s_or_b64 exec, exec, s[4:5]
	v_add_u32_e32 v15, 5, v54
	v_cndmask_b32_e64 v15, v15, 9, s[10:11]
	v_mul_hi_i32_i24_e32 v55, 0x6000, v15
	v_mul_i32_i24_e32 v54, 0x6000, v15
	v_lshl_add_u64 v[66:67], s[12:13], 0, v[54:55]
	v_lshl_add_u64 v[70:71], v[66:67], 0, s[42:43]
	v_lshl_add_u64 v[62:63], v[70:71], 0, v[36:37]
	global_load_dwordx4 v[76:79], v[16:17], off
	global_load_dwordx4 v[80:83], v[18:19], off
	v_lshl_add_u64 v[72:73], v[66:67], 0, v[36:37]
	global_load_dwordx4 v[84:87], v[62:63], off
	v_readlane_b32 s16, v254, 28
	global_load_dwordx4 v[88:91], v[72:73], off
	v_lshl_add_u64 v[140:141], v[70:71], 0, v[38:39]
	v_lshl_add_u64 v[142:143], v[70:71], 0, v[40:41]
	v_lshl_add_u64 v[160:161], v[70:71], 0, v[42:43]
	global_load_dwordx4 v[92:95], v[20:21], off
	global_load_dwordx4 v[96:99], v[22:23], off
	global_load_dwordx4 v[100:103], v[140:141], off
	global_load_dwordx4 v[104:107], v[72:73], off offset:1024
	global_load_dwordx4 v[108:111], v[24:25], off
	global_load_dwordx4 v[112:115], v[26:27], off
	global_load_dwordx4 v[116:119], v[142:143], off
	global_load_dwordx4 v[120:123], v[72:73], off offset:2048
	global_load_dwordx4 v[124:127], v[28:29], off
	global_load_dwordx4 v[128:131], v[30:31], off
	global_load_dwordx4 v[132:135], v[160:161], off
	global_load_dwordx4 v[136:139], v[72:73], off offset:3072
	v_pk_mul_f32 v[44:45], v[44:45], v[14:15] op_sel_hi:[1,0]
	v_pk_mul_f32 v[12:13], v[12:13], v[14:15] op_sel_hi:[1,0]
	v_readlane_b32 s22, v254, 34
	v_readlane_b32 s23, v254, 35
	v_pk_mul_f32 v[10:11], v[10:11], v[14:15] op_sel_hi:[1,0]
	v_pk_mul_f32 v[8:9], v[8:9], v[14:15] op_sel_hi:[1,0]
	v_lshl_add_u64 v[74:75], s[22:23], 0, v[34:35]
	v_add_co_u32_e32 v74, vcc, s31, v74
	v_pk_mul_f32 v[6:7], v[6:7], v[14:15] op_sel_hi:[1,0]
	s_nop 0
	v_addc_co_u32_e32 v75, vcc, 0, v75, vcc
	v_pk_mul_f32 v[4:5], v[4:5], v[14:15] op_sel_hi:[1,0]
	v_pk_mul_f32 v[2:3], v[2:3], v[14:15] op_sel_hi:[1,0]
	v_pk_mul_f32 v[0:1], v[0:1], v[14:15] op_sel_hi:[1,0]
	v_add_u32_e32 v53, s52, v53
	v_cmp_lt_i32_e32 vcc, s33, v53
	v_lshl_add_u64 v[32:33], v[32:33], 0, s[14:15]
	s_or_b64 s[38:39], vcc, s[38:39]
	v_lshl_add_u64 v[34:35], v[34:35], 0, s[24:25]
	v_readlane_b32 s17, v254, 29
	v_readlane_b32 s18, v254, 30
	v_readlane_b32 s19, v254, 31
	v_readlane_b32 s20, v254, 32
	v_readlane_b32 s21, v254, 33
	s_waitcnt vmcnt(14)
	v_pk_fma_f32 v[44:45], v[44:45], v[78:79], v[82:83]
	v_pk_fma_f32 v[12:13], v[12:13], v[76:77], v[80:81]
	s_waitcnt vmcnt(13)
	v_pk_add_f32 v[54:55], v[86:87], 1.0 op_sel_hi:[1,0]
	v_pk_add_f32 v[56:57], v[84:85], 1.0 op_sel_hi:[1,0]
	s_waitcnt vmcnt(12)
	v_pk_fma_f32 v[44:45], v[44:45], v[54:55], v[90:91]
	v_pk_fma_f32 v[12:13], v[12:13], v[56:57], v[88:89]
	s_nop 0
	v_cvt_pk_bf16_f32 v12, v12, v13
	v_cvt_pk_bf16_f32 v13, v44, v45
	global_store_dwordx2 v[74:75], v[12:13], off
	v_lshl_add_u64 v[12:13], v[70:71], 0, v[38:39]
	s_waitcnt vmcnt(11)
	v_pk_fma_f32 v[10:11], v[10:11], v[94:95], v[98:99]
	v_pk_fma_f32 v[8:9], v[8:9], v[92:93], v[96:97]
	s_waitcnt vmcnt(10)
	v_pk_add_f32 v[12:13], v[102:103], 1.0 op_sel_hi:[1,0]
	v_pk_add_f32 v[44:45], v[100:101], 1.0 op_sel_hi:[1,0]
	s_waitcnt vmcnt(9)
	v_pk_fma_f32 v[10:11], v[10:11], v[12:13], v[106:107]
	v_pk_fma_f32 v[8:9], v[8:9], v[44:45], v[104:105]
	v_lshl_add_u64 v[12:13], v[70:71], 0, v[40:41]
	v_cvt_pk_bf16_f32 v8, v8, v9
	v_cvt_pk_bf16_f32 v9, v10, v11
	global_store_dwordx2 v[74:75], v[8:9], off offset:512
	s_nop 0
	v_lshl_add_u64 v[12:13], v[70:71], 0, v[42:43]
	s_waitcnt vmcnt(8)
	v_pk_fma_f32 v[6:7], v[6:7], v[110:111], v[114:115]
	v_pk_fma_f32 v[4:5], v[4:5], v[108:109], v[112:113]
	s_waitcnt vmcnt(7)
	v_pk_add_f32 v[8:9], v[118:119], 1.0 op_sel_hi:[1,0]
	v_pk_add_f32 v[10:11], v[116:117], 1.0 op_sel_hi:[1,0]
	s_waitcnt vmcnt(6)
	v_pk_fma_f32 v[6:7], v[6:7], v[8:9], v[122:123]
	v_pk_fma_f32 v[4:5], v[4:5], v[10:11], v[120:121]
	s_nop 0
	v_cvt_pk_bf16_f32 v4, v4, v5
	v_cvt_pk_bf16_f32 v5, v6, v7
	global_store_dwordx2 v[74:75], v[4:5], off offset:1024
	s_nop 0
	s_waitcnt vmcnt(5)
	v_pk_fma_f32 v[2:3], v[2:3], v[126:127], v[130:131]
	v_pk_fma_f32 v[0:1], v[0:1], v[124:125], v[128:129]
	s_waitcnt vmcnt(4)
	v_pk_add_f32 v[4:5], v[134:135], 1.0 op_sel_hi:[1,0]
	v_pk_add_f32 v[6:7], v[132:133], 1.0 op_sel_hi:[1,0]
	s_waitcnt vmcnt(3)
	v_pk_fma_f32 v[2:3], v[2:3], v[4:5], v[138:139]
	v_pk_fma_f32 v[0:1], v[0:1], v[6:7], v[136:137]
	s_nop 0
	v_cvt_pk_bf16_f32 v0, v0, v1
	v_cvt_pk_bf16_f32 v1, v2, v3
	global_store_dwordx2 v[74:75], v[0:1], off offset:1536
	s_andn2_b64 exec, exec, s[38:39]
	s_cbranch_execz .LBB0_1853

.LBB0_2074:
	s_or_b64 exec, exec, s[4:5]
	v_add_u32_e32 v15, 10, v54
	v_cndmask_b32_e64 v15, v15, 14, s[12:13]
	v_readlane_b32 s36, v254, 28
	v_mul_hi_i32_i24_e32 v55, 0x6000, v15
	v_mul_i32_i24_e32 v54, 0x6000, v15
	v_readlane_b32 s42, v254, 34
	v_readlane_b32 s43, v254, 35
	v_pk_mul_f32 v[44:45], v[44:45], v[14:15] op_sel_hi:[1,0]
	v_pk_mul_f32 v[12:13], v[12:13], v[14:15] op_sel_hi:[1,0]
	v_lshl_add_u64 v[66:67], s[42:43], 0, v[54:55]
	v_lshl_add_u64 v[70:71], v[66:67], 0, s[24:25]
	v_lshl_add_u64 v[62:63], v[70:71], 0, v[36:37]
	global_load_dwordx4 v[76:79], v[16:17], off
	global_load_dwordx4 v[80:83], v[18:19], off
	v_lshl_add_u64 v[72:73], v[66:67], 0, v[36:37]
	global_load_dwordx4 v[84:87], v[62:63], off
	v_lshl_add_u64 v[74:75], s[42:43], 0, v[34:35]
	global_load_dwordx4 v[88:91], v[72:73], off
	v_lshl_add_u64 v[140:141], v[70:71], 0, v[38:39]
	v_lshl_add_u64 v[142:143], v[70:71], 0, v[40:41]
	v_lshl_add_u64 v[160:161], v[70:71], 0, v[42:43]
	global_load_dwordx4 v[92:95], v[20:21], off
	global_load_dwordx4 v[96:99], v[22:23], off
	global_load_dwordx4 v[100:103], v[140:141], off
	global_load_dwordx4 v[104:107], v[72:73], off offset:1024
	global_load_dwordx4 v[108:111], v[24:25], off
	global_load_dwordx4 v[112:115], v[26:27], off
	global_load_dwordx4 v[116:119], v[142:143], off
	global_load_dwordx4 v[120:123], v[72:73], off offset:2048
	global_load_dwordx4 v[124:127], v[28:29], off
	global_load_dwordx4 v[128:131], v[30:31], off
	global_load_dwordx4 v[132:135], v[160:161], off
	global_load_dwordx4 v[136:139], v[72:73], off offset:3072
	v_add_co_u32_e32 v74, vcc, s29, v74
	v_pk_mul_f32 v[10:11], v[10:11], v[14:15] op_sel_hi:[1,0]
	s_nop 0
	v_addc_co_u32_e32 v75, vcc, 0, v75, vcc
	v_pk_mul_f32 v[8:9], v[8:9], v[14:15] op_sel_hi:[1,0]
	v_pk_mul_f32 v[6:7], v[6:7], v[14:15] op_sel_hi:[1,0]
	v_pk_mul_f32 v[4:5], v[4:5], v[14:15] op_sel_hi:[1,0]
	v_pk_mul_f32 v[2:3], v[2:3], v[14:15] op_sel_hi:[1,0]
	v_pk_mul_f32 v[0:1], v[0:1], v[14:15] op_sel_hi:[1,0]
	v_add_u32_e32 v53, s52, v53
	v_cmp_lt_i32_e32 vcc, s30, v53
	v_lshl_add_u64 v[32:33], v[32:33], 0, s[14:15]
	s_or_b64 s[18:19], vcc, s[18:19]
	v_lshl_add_u64 v[34:35], v[34:35], 0, s[16:17]
	v_readlane_b32 s37, v254, 29
	v_readlane_b32 s38, v254, 30
	v_readlane_b32 s39, v254, 31
	v_readlane_b32 s40, v254, 32
	v_readlane_b32 s41, v254, 33
	s_waitcnt vmcnt(14)
	v_pk_fma_f32 v[44:45], v[44:45], v[78:79], v[82:83]
	v_pk_fma_f32 v[12:13], v[12:13], v[76:77], v[80:81]
	s_waitcnt vmcnt(13)
	v_pk_add_f32 v[54:55], v[86:87], 1.0 op_sel_hi:[1,0]
	v_pk_add_f32 v[56:57], v[84:85], 1.0 op_sel_hi:[1,0]
	s_waitcnt vmcnt(12)
	v_pk_fma_f32 v[44:45], v[44:45], v[54:55], v[90:91]
	v_pk_fma_f32 v[12:13], v[12:13], v[56:57], v[88:89]
	s_nop 0
	v_cvt_pk_bf16_f32 v12, v12, v13
	v_cvt_pk_bf16_f32 v13, v44, v45
	global_store_dwordx2 v[74:75], v[12:13], off
	v_lshl_add_u64 v[12:13], v[70:71], 0, v[38:39]
	s_waitcnt vmcnt(11)
	v_pk_fma_f32 v[10:11], v[10:11], v[94:95], v[98:99]
	v_pk_fma_f32 v[8:9], v[8:9], v[92:93], v[96:97]
	s_waitcnt vmcnt(10)
	v_pk_add_f32 v[12:13], v[102:103], 1.0 op_sel_hi:[1,0]
	v_pk_add_f32 v[44:45], v[100:101], 1.0 op_sel_hi:[1,0]
	s_waitcnt vmcnt(9)
	v_pk_fma_f32 v[10:11], v[10:11], v[12:13], v[106:107]
	v_pk_fma_f32 v[8:9], v[8:9], v[44:45], v[104:105]
	v_lshl_add_u64 v[12:13], v[70:71], 0, v[40:41]
	v_cvt_pk_bf16_f32 v8, v8, v9
	v_cvt_pk_bf16_f32 v9, v10, v11
	global_store_dwordx2 v[74:75], v[8:9], off offset:512
	s_nop 0
	v_lshl_add_u64 v[12:13], v[70:71], 0, v[42:43]
	s_waitcnt vmcnt(8)
	v_pk_fma_f32 v[6:7], v[6:7], v[110:111], v[114:115]
	v_pk_fma_f32 v[4:5], v[4:5], v[108:109], v[112:113]
	s_waitcnt vmcnt(7)
	v_pk_add_f32 v[8:9], v[118:119], 1.0 op_sel_hi:[1,0]
	v_pk_add_f32 v[10:11], v[116:117], 1.0 op_sel_hi:[1,0]
	s_waitcnt vmcnt(6)
	v_pk_fma_f32 v[6:7], v[6:7], v[8:9], v[122:123]
	v_pk_fma_f32 v[4:5], v[4:5], v[10:11], v[120:121]
	s_nop 0
	v_cvt_pk_bf16_f32 v4, v4, v5
	v_cvt_pk_bf16_f32 v5, v6, v7
	global_store_dwordx2 v[74:75], v[4:5], off offset:1024
	s_nop 0
	s_waitcnt vmcnt(5)
	v_pk_fma_f32 v[2:3], v[2:3], v[126:127], v[130:131]
	v_pk_fma_f32 v[0:1], v[0:1], v[124:125], v[128:129]
	s_waitcnt vmcnt(4)
	v_pk_add_f32 v[4:5], v[134:135], 1.0 op_sel_hi:[1,0]
	v_pk_add_f32 v[6:7], v[132:133], 1.0 op_sel_hi:[1,0]
	s_waitcnt vmcnt(3)
	v_pk_fma_f32 v[2:3], v[2:3], v[4:5], v[138:139]
	v_pk_fma_f32 v[0:1], v[0:1], v[6:7], v[136:137]
	s_nop 0
	v_cvt_pk_bf16_f32 v0, v0, v1
	v_cvt_pk_bf16_f32 v1, v2, v3
	global_store_dwordx2 v[74:75], v[0:1], off offset:1536
	s_andn2_b64 exec, exec, s[18:19]
	s_cbranch_execz .LBB0_2081

.LBB0_2881:
	s_or_b64 exec, exec, s[4:5]
	v_add_u32_e32 v15, 10, v54
	v_cndmask_b32_e64 v15, v15, 14, s[12:13]
	v_mul_hi_i32_i24_e32 v55, 0x6000, v15
	v_mul_i32_i24_e32 v54, 0x6000, v15
	v_lshl_add_u64 v[66:67], s[14:15], 0, v[54:55]
	v_lshl_add_u64 v[70:71], v[66:67], 0, s[22:23]
	v_lshl_add_u64 v[62:63], v[70:71], 0, v[36:37]
	global_load_dwordx4 v[76:79], v[16:17], off
	global_load_dwordx4 v[80:83], v[18:19], off
	v_lshl_add_u64 v[72:73], v[66:67], 0, v[36:37]
	global_load_dwordx4 v[84:87], v[62:63], off
	v_pk_mul_f32 v[44:45], v[44:45], v[14:15] op_sel_hi:[1,0]
	global_load_dwordx4 v[88:91], v[72:73], off
	v_lshl_add_u64 v[140:141], v[70:71], 0, v[38:39]
	v_lshl_add_u64 v[142:143], v[70:71], 0, v[40:41]
	v_lshl_add_u64 v[160:161], v[70:71], 0, v[42:43]
	global_load_dwordx4 v[92:95], v[20:21], off
	global_load_dwordx4 v[96:99], v[22:23], off
	global_load_dwordx4 v[100:103], v[140:141], off
	global_load_dwordx4 v[104:107], v[72:73], off offset:1024
	global_load_dwordx4 v[108:111], v[24:25], off
	global_load_dwordx4 v[112:115], v[26:27], off
	global_load_dwordx4 v[116:119], v[142:143], off
	global_load_dwordx4 v[120:123], v[72:73], off offset:2048
	global_load_dwordx4 v[124:127], v[28:29], off
	global_load_dwordx4 v[128:131], v[30:31], off
	global_load_dwordx4 v[132:135], v[160:161], off
	global_load_dwordx4 v[136:139], v[72:73], off offset:3072
	v_pk_mul_f32 v[12:13], v[12:13], v[14:15] op_sel_hi:[1,0]
	v_lshl_add_u64 v[74:75], s[90:91], 0, v[34:35]
	v_add_co_u32_e32 v74, vcc, s25, v74
	v_pk_mul_f32 v[10:11], v[10:11], v[14:15] op_sel_hi:[1,0]
	s_nop 0
	v_addc_co_u32_e32 v75, vcc, 0, v75, vcc
	v_pk_mul_f32 v[8:9], v[8:9], v[14:15] op_sel_hi:[1,0]
	v_pk_mul_f32 v[6:7], v[6:7], v[14:15] op_sel_hi:[1,0]
	v_pk_mul_f32 v[4:5], v[4:5], v[14:15] op_sel_hi:[1,0]
	v_pk_mul_f32 v[2:3], v[2:3], v[14:15] op_sel_hi:[1,0]
	v_pk_mul_f32 v[0:1], v[0:1], v[14:15] op_sel_hi:[1,0]
	v_add_u32_e32 v53, s52, v53
	v_cmp_lt_i32_e32 vcc, s26, v53
	v_lshl_add_u64 v[32:33], v[32:33], 0, s[16:17]
	s_or_b64 s[20:21], vcc, s[20:21]
	v_lshl_add_u64 v[34:35], v[34:35], 0, s[18:19]
	s_waitcnt vmcnt(14)
	v_pk_fma_f32 v[44:45], v[44:45], v[78:79], v[82:83]
	v_pk_fma_f32 v[12:13], v[12:13], v[76:77], v[80:81]
	s_waitcnt vmcnt(13)
	v_pk_add_f32 v[54:55], v[86:87], 1.0 op_sel_hi:[1,0]
	v_pk_add_f32 v[56:57], v[84:85], 1.0 op_sel_hi:[1,0]
	s_waitcnt vmcnt(12)
	v_pk_fma_f32 v[44:45], v[44:45], v[54:55], v[90:91]
	v_pk_fma_f32 v[12:13], v[12:13], v[56:57], v[88:89]
	s_nop 0
	v_cvt_pk_bf16_f32 v12, v12, v13
	v_cvt_pk_bf16_f32 v13, v44, v45
	global_store_dwordx2 v[74:75], v[12:13], off
	v_lshl_add_u64 v[12:13], v[70:71], 0, v[38:39]
	s_waitcnt vmcnt(11)
	v_pk_fma_f32 v[10:11], v[10:11], v[94:95], v[98:99]
	v_pk_fma_f32 v[8:9], v[8:9], v[92:93], v[96:97]
	s_waitcnt vmcnt(10)
	v_pk_add_f32 v[12:13], v[102:103], 1.0 op_sel_hi:[1,0]
	v_pk_add_f32 v[44:45], v[100:101], 1.0 op_sel_hi:[1,0]
	s_waitcnt vmcnt(9)
	v_pk_fma_f32 v[10:11], v[10:11], v[12:13], v[106:107]
	v_pk_fma_f32 v[8:9], v[8:9], v[44:45], v[104:105]
	v_lshl_add_u64 v[12:13], v[70:71], 0, v[40:41]
	v_cvt_pk_bf16_f32 v8, v8, v9
	v_cvt_pk_bf16_f32 v9, v10, v11
	global_store_dwordx2 v[74:75], v[8:9], off offset:512
	s_nop 0
	v_lshl_add_u64 v[12:13], v[70:71], 0, v[42:43]
	s_waitcnt vmcnt(8)
	v_pk_fma_f32 v[6:7], v[6:7], v[110:111], v[114:115]
	v_pk_fma_f32 v[4:5], v[4:5], v[108:109], v[112:113]
	s_waitcnt vmcnt(7)
	v_pk_add_f32 v[8:9], v[118:119], 1.0 op_sel_hi:[1,0]
	v_pk_add_f32 v[10:11], v[116:117], 1.0 op_sel_hi:[1,0]
	s_waitcnt vmcnt(6)
	v_pk_fma_f32 v[6:7], v[6:7], v[8:9], v[122:123]
	v_pk_fma_f32 v[4:5], v[4:5], v[10:11], v[120:121]
	s_nop 0
	v_cvt_pk_bf16_f32 v4, v4, v5
	v_cvt_pk_bf16_f32 v5, v6, v7
	global_store_dwordx2 v[74:75], v[4:5], off offset:1024
	s_nop 0
	s_waitcnt vmcnt(5)
	v_pk_fma_f32 v[2:3], v[2:3], v[126:127], v[130:131]
	v_pk_fma_f32 v[0:1], v[0:1], v[124:125], v[128:129]
	s_waitcnt vmcnt(4)
	v_pk_add_f32 v[4:5], v[134:135], 1.0 op_sel_hi:[1,0]
	v_pk_add_f32 v[6:7], v[132:133], 1.0 op_sel_hi:[1,0]
	s_waitcnt vmcnt(3)
	v_pk_fma_f32 v[2:3], v[2:3], v[4:5], v[138:139]
	v_pk_fma_f32 v[0:1], v[0:1], v[6:7], v[136:137]
	s_nop 0
	v_cvt_pk_bf16_f32 v0, v0, v1
	v_cvt_pk_bf16_f32 v1, v2, v3
	global_store_dwordx2 v[74:75], v[0:1], off offset:1536
	s_andn2_b64 exec, exec, s[20:21]
	s_cbranch_execz .LBB0_2888

.LBB0_3109:
	s_or_b64 exec, exec, s[4:5]
	v_add_u32_e32 v15, 15, v54
	v_cndmask_b32_e64 v15, v15, 19, s[10:11]
	v_mul_hi_i32_i24_e32 v55, 0x6000, v15
	v_mul_i32_i24_e32 v54, 0x6000, v15
	v_lshl_add_u64 v[66:67], s[90:91], 0, v[54:55]
	v_lshl_add_u64 v[70:71], v[66:67], 0, s[18:19]
	v_lshl_add_u64 v[62:63], v[70:71], 0, v[36:37]
	global_load_dwordx4 v[76:79], v[16:17], off
	global_load_dwordx4 v[80:83], v[18:19], off
	v_lshl_add_u64 v[72:73], v[66:67], 0, v[36:37]
	global_load_dwordx4 v[84:87], v[62:63], off
	v_pk_mul_f32 v[44:45], v[44:45], v[14:15] op_sel_hi:[1,0]
	global_load_dwordx4 v[88:91], v[72:73], off
	v_lshl_add_u64 v[140:141], v[70:71], 0, v[38:39]
	v_lshl_add_u64 v[142:143], v[70:71], 0, v[40:41]
	v_lshl_add_u64 v[156:157], v[70:71], 0, v[42:43]
	global_load_dwordx4 v[92:95], v[20:21], off
	global_load_dwordx4 v[96:99], v[22:23], off
	global_load_dwordx4 v[100:103], v[140:141], off
	global_load_dwordx4 v[104:107], v[72:73], off offset:1024
	global_load_dwordx4 v[108:111], v[24:25], off
	global_load_dwordx4 v[112:115], v[26:27], off
	global_load_dwordx4 v[116:119], v[142:143], off
	global_load_dwordx4 v[120:123], v[72:73], off offset:2048
	global_load_dwordx4 v[124:127], v[28:29], off
	global_load_dwordx4 v[128:131], v[30:31], off
	global_load_dwordx4 v[132:135], v[156:157], off
	global_load_dwordx4 v[136:139], v[72:73], off offset:3072
	v_pk_mul_f32 v[12:13], v[12:13], v[14:15] op_sel_hi:[1,0]
	v_lshl_add_u64 v[74:75], s[90:91], 0, v[34:35]
	v_add_co_u32_e32 v74, vcc, s23, v74
	v_pk_mul_f32 v[10:11], v[10:11], v[14:15] op_sel_hi:[1,0]
	s_nop 0
	v_addc_co_u32_e32 v75, vcc, 0, v75, vcc
	v_pk_mul_f32 v[8:9], v[8:9], v[14:15] op_sel_hi:[1,0]
	v_pk_mul_f32 v[6:7], v[6:7], v[14:15] op_sel_hi:[1,0]
	v_pk_mul_f32 v[4:5], v[4:5], v[14:15] op_sel_hi:[1,0]
	v_pk_mul_f32 v[2:3], v[2:3], v[14:15] op_sel_hi:[1,0]
	v_pk_mul_f32 v[0:1], v[0:1], v[14:15] op_sel_hi:[1,0]
	v_add_u32_e32 v53, s52, v53
	v_cmp_lt_i32_e32 vcc, s24, v53
	v_lshl_add_u64 v[32:33], v[32:33], 0, s[12:13]
	s_or_b64 s[16:17], vcc, s[16:17]
	v_lshl_add_u64 v[34:35], v[34:35], 0, s[14:15]
	s_waitcnt vmcnt(14)
	v_pk_fma_f32 v[44:45], v[44:45], v[78:79], v[82:83]
	v_pk_fma_f32 v[12:13], v[12:13], v[76:77], v[80:81]
	s_waitcnt vmcnt(13)
	v_pk_add_f32 v[54:55], v[86:87], 1.0 op_sel_hi:[1,0]
	v_pk_add_f32 v[56:57], v[84:85], 1.0 op_sel_hi:[1,0]
	s_waitcnt vmcnt(12)
	v_pk_fma_f32 v[44:45], v[44:45], v[54:55], v[90:91]
	v_pk_fma_f32 v[12:13], v[12:13], v[56:57], v[88:89]
	s_nop 0
	v_cvt_pk_bf16_f32 v12, v12, v13
	v_cvt_pk_bf16_f32 v13, v44, v45
	global_store_dwordx2 v[74:75], v[12:13], off
	v_lshl_add_u64 v[12:13], v[70:71], 0, v[38:39]
	s_waitcnt vmcnt(11)
	v_pk_fma_f32 v[10:11], v[10:11], v[94:95], v[98:99]
	v_pk_fma_f32 v[8:9], v[8:9], v[92:93], v[96:97]
	s_waitcnt vmcnt(10)
	v_pk_add_f32 v[12:13], v[102:103], 1.0 op_sel_hi:[1,0]
	v_pk_add_f32 v[44:45], v[100:101], 1.0 op_sel_hi:[1,0]
	s_waitcnt vmcnt(9)
	v_pk_fma_f32 v[10:11], v[10:11], v[12:13], v[106:107]
	v_pk_fma_f32 v[8:9], v[8:9], v[44:45], v[104:105]
	v_lshl_add_u64 v[12:13], v[70:71], 0, v[40:41]
	v_cvt_pk_bf16_f32 v8, v8, v9
	v_cvt_pk_bf16_f32 v9, v10, v11
	global_store_dwordx2 v[74:75], v[8:9], off offset:512
	s_nop 0
	v_lshl_add_u64 v[12:13], v[70:71], 0, v[42:43]
	s_waitcnt vmcnt(8)
	v_pk_fma_f32 v[6:7], v[6:7], v[110:111], v[114:115]
	v_pk_fma_f32 v[4:5], v[4:5], v[108:109], v[112:113]
	s_waitcnt vmcnt(7)
	v_pk_add_f32 v[8:9], v[118:119], 1.0 op_sel_hi:[1,0]
	v_pk_add_f32 v[10:11], v[116:117], 1.0 op_sel_hi:[1,0]
	s_waitcnt vmcnt(6)
	v_pk_fma_f32 v[6:7], v[6:7], v[8:9], v[122:123]
	v_pk_fma_f32 v[4:5], v[4:5], v[10:11], v[120:121]
	s_nop 0
	v_cvt_pk_bf16_f32 v4, v4, v5
	v_cvt_pk_bf16_f32 v5, v6, v7
	global_store_dwordx2 v[74:75], v[4:5], off offset:1024
	s_nop 0
	s_waitcnt vmcnt(5)
	v_pk_fma_f32 v[2:3], v[2:3], v[126:127], v[130:131]
	v_pk_fma_f32 v[0:1], v[0:1], v[124:125], v[128:129]
	s_waitcnt vmcnt(4)
	v_pk_add_f32 v[4:5], v[134:135], 1.0 op_sel_hi:[1,0]
	v_pk_add_f32 v[6:7], v[132:133], 1.0 op_sel_hi:[1,0]
	s_waitcnt vmcnt(3)
	v_pk_fma_f32 v[2:3], v[2:3], v[4:5], v[138:139]
	v_pk_fma_f32 v[0:1], v[0:1], v[6:7], v[136:137]
	s_nop 0
	v_cvt_pk_bf16_f32 v0, v0, v1
	v_cvt_pk_bf16_f32 v1, v2, v3
	global_store_dwordx2 v[74:75], v[0:1], off offset:1536
	s_andn2_b64 exec, exec, s[16:17]
	s_cbranch_execz .LBB0_3116

.LBB0_3595:
	s_or_b64 exec, exec, s[4:5]
	v_add_u32_e32 v15, 15, v54
	v_cndmask_b32_e64 v15, v15, 19, s[8:9]
	v_mul_hi_i32_i24_e32 v55, 0x6000, v15
	v_mul_i32_i24_e32 v54, 0x6000, v15
	v_lshl_add_u64 v[66:67], s[10:11], 0, v[54:55]
	v_lshl_add_u64 v[70:71], v[66:67], 0, s[18:19]
	v_lshl_add_u64 v[62:63], v[70:71], 0, v[36:37]
	global_load_dwordx4 v[76:79], v[16:17], off
	global_load_dwordx4 v[80:83], v[18:19], off
	v_lshl_add_u64 v[72:73], v[66:67], 0, v[36:37]
	global_load_dwordx4 v[84:87], v[62:63], off
	v_pk_mul_f32 v[44:45], v[44:45], v[14:15] op_sel_hi:[1,0]
	global_load_dwordx4 v[88:91], v[72:73], off
	v_lshl_add_u64 v[140:141], v[70:71], 0, v[38:39]
	v_lshl_add_u64 v[142:143], v[70:71], 0, v[40:41]
	v_lshl_add_u64 v[156:157], v[70:71], 0, v[42:43]
	global_load_dwordx4 v[92:95], v[20:21], off
	global_load_dwordx4 v[96:99], v[22:23], off
	global_load_dwordx4 v[100:103], v[140:141], off
	global_load_dwordx4 v[104:107], v[72:73], off offset:1024
	global_load_dwordx4 v[108:111], v[24:25], off
	global_load_dwordx4 v[112:115], v[26:27], off
	global_load_dwordx4 v[116:119], v[142:143], off
	global_load_dwordx4 v[120:123], v[72:73], off offset:2048
	global_load_dwordx4 v[124:127], v[28:29], off
	global_load_dwordx4 v[128:131], v[30:31], off
	global_load_dwordx4 v[132:135], v[156:157], off
	global_load_dwordx4 v[136:139], v[72:73], off offset:3072
	v_pk_mul_f32 v[12:13], v[12:13], v[14:15] op_sel_hi:[1,0]
	v_lshl_add_u64 v[74:75], s[90:91], 0, v[34:35]
	v_add_co_u32_e32 v74, vcc, s25, v74
	v_pk_mul_f32 v[10:11], v[10:11], v[14:15] op_sel_hi:[1,0]
	s_nop 0
	v_addc_co_u32_e32 v75, vcc, 0, v75, vcc
	v_pk_mul_f32 v[8:9], v[8:9], v[14:15] op_sel_hi:[1,0]
	v_pk_mul_f32 v[6:7], v[6:7], v[14:15] op_sel_hi:[1,0]
	v_pk_mul_f32 v[4:5], v[4:5], v[14:15] op_sel_hi:[1,0]
	v_pk_mul_f32 v[2:3], v[2:3], v[14:15] op_sel_hi:[1,0]
	v_pk_mul_f32 v[0:1], v[0:1], v[14:15] op_sel_hi:[1,0]
	v_add_u32_e32 v53, s52, v53
	v_cmp_lt_i32_e32 vcc, s26, v53
	v_lshl_add_u64 v[32:33], v[32:33], 0, s[12:13]
	s_or_b64 s[16:17], vcc, s[16:17]
	v_lshl_add_u64 v[34:35], v[34:35], 0, s[14:15]
	s_waitcnt vmcnt(14)
	v_pk_fma_f32 v[44:45], v[44:45], v[78:79], v[82:83]
	v_pk_fma_f32 v[12:13], v[12:13], v[76:77], v[80:81]
	s_waitcnt vmcnt(13)
	v_pk_add_f32 v[54:55], v[86:87], 1.0 op_sel_hi:[1,0]
	v_pk_add_f32 v[56:57], v[84:85], 1.0 op_sel_hi:[1,0]
	s_waitcnt vmcnt(12)
	v_pk_fma_f32 v[44:45], v[44:45], v[54:55], v[90:91]
	v_pk_fma_f32 v[12:13], v[12:13], v[56:57], v[88:89]
	s_nop 0
	v_cvt_pk_bf16_f32 v12, v12, v13
	v_cvt_pk_bf16_f32 v13, v44, v45
	global_store_dwordx2 v[74:75], v[12:13], off
	v_lshl_add_u64 v[12:13], v[70:71], 0, v[38:39]
	s_waitcnt vmcnt(11)
	v_pk_fma_f32 v[10:11], v[10:11], v[94:95], v[98:99]
	v_pk_fma_f32 v[8:9], v[8:9], v[92:93], v[96:97]
	s_waitcnt vmcnt(10)
	v_pk_add_f32 v[12:13], v[102:103], 1.0 op_sel_hi:[1,0]
	v_pk_add_f32 v[44:45], v[100:101], 1.0 op_sel_hi:[1,0]
	s_waitcnt vmcnt(9)
	v_pk_fma_f32 v[10:11], v[10:11], v[12:13], v[106:107]
	v_pk_fma_f32 v[8:9], v[8:9], v[44:45], v[104:105]
	v_lshl_add_u64 v[12:13], v[70:71], 0, v[40:41]
	v_cvt_pk_bf16_f32 v8, v8, v9
	v_cvt_pk_bf16_f32 v9, v10, v11
	global_store_dwordx2 v[74:75], v[8:9], off offset:512
	s_nop 0
	v_lshl_add_u64 v[12:13], v[70:71], 0, v[42:43]
	s_waitcnt vmcnt(8)
	v_pk_fma_f32 v[6:7], v[6:7], v[110:111], v[114:115]
	v_pk_fma_f32 v[4:5], v[4:5], v[108:109], v[112:113]
	s_waitcnt vmcnt(7)
	v_pk_add_f32 v[8:9], v[118:119], 1.0 op_sel_hi:[1,0]
	v_pk_add_f32 v[10:11], v[116:117], 1.0 op_sel_hi:[1,0]
	s_waitcnt vmcnt(6)
	v_pk_fma_f32 v[6:7], v[6:7], v[8:9], v[122:123]
	v_pk_fma_f32 v[4:5], v[4:5], v[10:11], v[120:121]
	s_nop 0
	v_cvt_pk_bf16_f32 v4, v4, v5
	v_cvt_pk_bf16_f32 v5, v6, v7
	global_store_dwordx2 v[74:75], v[4:5], off offset:1024
	s_nop 0
	s_waitcnt vmcnt(5)
	v_pk_fma_f32 v[2:3], v[2:3], v[126:127], v[130:131]
	v_pk_fma_f32 v[0:1], v[0:1], v[124:125], v[128:129]
	s_waitcnt vmcnt(4)
	v_pk_add_f32 v[4:5], v[134:135], 1.0 op_sel_hi:[1,0]
	v_pk_add_f32 v[6:7], v[132:133], 1.0 op_sel_hi:[1,0]
	s_waitcnt vmcnt(3)
	v_pk_fma_f32 v[2:3], v[2:3], v[4:5], v[138:139]
	v_pk_fma_f32 v[0:1], v[0:1], v[6:7], v[136:137]
	s_nop 0
	v_cvt_pk_bf16_f32 v0, v0, v1
	v_cvt_pk_bf16_f32 v1, v2, v3
	global_store_dwordx2 v[74:75], v[0:1], off offset:1536
	s_andn2_b64 exec, exec, s[16:17]
	s_cbranch_execz .LBB0_3602
